# out-proj L0 residual epilogue: next-batch x loads deferred behind the gate loads, counted vmcnt(8) instead of vmcnt(0); flat->global
# baseline (speedup 1.0000x reference)
; #define EPIRES_LOAD(q_, buf_) do { const int bj_ = (q_) >> 1, ai_ = (q_) & 1; \
;             _Pragma("unroll") for (int m = 0; m < 4; ++m) { const float* xp = Xin + (size_t)(row0 + ai_ * HALF + m * 16) * D + col0 + bj_ * HALF; xa[buf_][m] = *(const f32x4*)xp; xb[buf_][m] = *(const f32x4*)(xp + 4); } } while (0)
;     __device__ __forceinline__ void operator()(const f32x4 (&acc)[2][2][4][2], const Unit& u, int wr, int wc, int fr, int fq) const {
;     ...
;         const int row0 = u.pm * BM + wr * 64 + fr, col0 = u.pn * BM + wc * 32 + 8 * fq;
;         const float* gp = gate + (size_t)((u.pm * BM) >> 11) * 6144 + col0;
;         f32x2_t st[2][4];
; #pragma unroll
;         for (int ai = 0; ai < 2; ++ai)
; #pragma unroll
;             for (int m = 0; m < 4; ++m) st[ai][m] = stats ? *(const f32x2_t*)(stats + 2 * (row0 + ai * HALF + m * 16)) : (f32x2_t){0.f, 1.f};
;         f32x4 xa[2][4], xb[2][4];
;     ...
;         EPIRES_LOAD(0, 0);
; #pragma unroll
;         for (int q = 0; q < 4; ++q) { const int bj = q >> 1, ai = q & 1, co = col0 + bj * HALF, cb = q & 1;
;             if (q + 1 < 4) EPIRES_LOAD(q + 1, cb ^ 1);
;             const f32x4 g0 = *(const f32x4*)(gp + bj * HALF), g1 = *(const f32x4*)(gp + bj * HALF + 4);
;             f32x4 w0 = {1.f, 1.f, 1.f, 1.f}, w1 = w0, b0 = {0.f, 0.f, 0.f, 0.f}, b1 = b0;
;             if (stats) { w0 = *(const f32x4*)(lw + co); w1 = *(const f32x4*)(lw + co + 4); b0 = *(const f32x4*)(lb + co); b1 = *(const f32x4*)(lb + co + 4); }
; #pragma unroll
;             for (int m = 0; m < 4; ++m) { float* op = Xout + (size_t)(row0 + ai * HALF + m * 16) * D + co;
;                 f32x4 x0 = xa[cb][m], x1 = xb[cb][m];
;                 if (stats) { x0 = (x0 - st[ai][m].x) * st[ai][m].y * w0 + b0; x1 = (x1 - st[ai][m].x) * st[ai][m].y * w1 + b1; }
;                 *(f32x4*)op = x0 * ALPHA + g0 * acc[ai][bj][m][0]; *(f32x4*)(op + 4) = x1 * ALPHA + g1 * acc[ai][bj][m][1]; } }
.LBB0_480:
	v_lshl_add_u32 v130, s43, 8, v251
	v_lshl_add_u32 v128, s42, 8, v249
	v_ashrrev_i32_e32 v131, 31, v130
	v_lshlrev_b64 v[216:217], 2, v[130:131]
	v_or_b32_e32 v130, 16, v128
	v_ashrrev_i32_e32 v129, 31, v128
	v_ashrrev_i32_e32 v131, 31, v130
	s_ashr_i32 s29, s42, 3
	v_lshlrev_b64 v[214:215], 12, v[128:129]
	v_lshlrev_b64 v[246:247], 12, v[130:131]
	v_or_b32_e32 v130, 32, v128
	v_or_b32_e32 v128, 48, v128
	s_mul_hi_i32 s31, s29, 0x6000
	s_mulk_i32 s29, 0x6000
	v_ashrrev_i32_e32 v131, 31, v130
	v_ashrrev_i32_e32 v129, 31, v128
	s_add_u32 s42, s52, s29
	v_lshl_add_u64 v[140:141], s[6:7], 0, v[216:217]
	v_lshlrev_b64 v[244:245], 12, v[130:131]
	v_lshlrev_b64 v[226:227], 12, v[128:129]
	v_lshl_add_u64 v[242:243], v[214:215], 0, s[18:19]
	v_lshl_add_u64 v[240:241], v[214:215], 0, s[20:21]
	v_lshl_add_u64 v[238:239], v[214:215], 0, s[22:23]
	v_lshl_add_u64 v[236:237], v[214:215], 0, s[24:25]
	s_addc_u32 s43, s53, s31
	v_lshl_add_u64 v[218:219], v[140:141], 0, v[214:215]
	v_lshl_add_u64 v[220:221], v[140:141], 0, v[246:247]
	v_lshl_add_u64 v[222:223], v[140:141], 0, v[244:245]
	v_lshl_add_u64 v[224:225], v[140:141], 0, v[226:227]
	v_lshl_add_u64 v[228:229], v[140:141], 0, v[242:243]
	v_lshl_add_u64 v[230:231], v[140:141], 0, v[240:241]
	v_lshl_add_u64 v[232:233], v[140:141], 0, v[238:239]
	v_lshl_add_u64 v[234:235], v[140:141], 0, v[236:237]
	global_load_dwordx4 v[196:199], v[218:219], off
	global_load_dwordx4 v[192:195], v[218:219], off offset:16
	global_load_dwordx4 v[188:191], v[220:221], off
	global_load_dwordx4 v[184:187], v[220:221], off offset:16
	global_load_dwordx4 v[172:175], v[222:223], off
	global_load_dwordx4 v[136:139], v[222:223], off offset:16
	global_load_dwordx4 v[132:135], v[224:225], off
	global_load_dwordx4 v[128:131], v[224:225], off offset:16
	v_lshl_add_u64 v[212:213], s[42:43], 0, v[216:217]
	global_load_dwordx4 v[180:183], v[212:213], off
	global_load_dwordx4 v[176:179], v[212:213], off offset:16
	v_lshl_add_u64 v[214:215], s[10:11], 0, v[214:215]
	v_lshl_add_u64 v[214:215], v[214:215], 0, v[216:217]
	s_mov_b64 s[42:43], -1
	s_andn2_b64 vcc, exec, s[4:5]
	global_load_dwordx4 v[168:171], v[228:229], off
	global_load_dwordx4 v[164:167], v[228:229], off offset:16
	global_load_dwordx4 v[160:163], v[230:231], off
	global_load_dwordx4 v[156:159], v[230:231], off offset:16
	global_load_dwordx4 v[152:155], v[232:233], off
	global_load_dwordx4 v[148:151], v[232:233], off offset:16
	global_load_dwordx4 v[144:147], v[234:235], off
	global_load_dwordx4 v[140:143], v[234:235], off offset:16
	s_waitcnt vmcnt(8) lgkmcnt(0)
	v_pk_mul_f32 v[126:127], v[126:127], v[182:183]
	v_pk_mul_f32 v[122:123], v[122:123], v[178:179]
	v_pk_mul_f32 v[120:121], v[120:121], v[176:177]
	v_pk_fma_f32 v[122:123], v[194:195], s[26:27], v[122:123] op_sel_hi:[1,0,1]
	v_pk_fma_f32 v[120:121], v[192:193], s[26:27], v[120:121] op_sel_hi:[1,0,1]
	global_store_dwordx4 v[214:215], v[120:123], off offset:16
	v_pk_mul_f32 v[114:115], v[114:115], v[178:179]
	v_pk_mul_f32 v[112:113], v[112:113], v[176:177]
	v_lshl_add_u64 v[120:121], s[10:11], 0, v[246:247]
	v_lshl_add_u64 v[192:193], v[120:121], 0, v[216:217]
	v_pk_fma_f32 v[114:115], v[186:187], s[26:27], v[114:115] op_sel_hi:[1,0,1]
	v_pk_fma_f32 v[112:113], v[184:185], s[26:27], v[112:113] op_sel_hi:[1,0,1]
	global_store_dwordx4 v[192:193], v[112:115], off offset:16
	v_pk_mul_f32 v[106:107], v[106:107], v[178:179]
	v_pk_mul_f32 v[104:105], v[104:105], v[176:177]
	v_lshl_add_u64 v[112:113], s[10:11], 0, v[244:245]
	v_lshl_add_u64 v[184:185], v[112:113], 0, v[216:217]
	v_pk_fma_f32 v[106:107], v[138:139], s[26:27], v[106:107] op_sel_hi:[1,0,1]
	v_pk_fma_f32 v[104:105], v[136:137], s[26:27], v[104:105] op_sel_hi:[1,0,1]
	v_pk_mul_f32 v[124:125], v[124:125], v[180:181]
	v_pk_mul_f32 v[118:119], v[118:119], v[182:183]
	v_pk_mul_f32 v[116:117], v[116:117], v[180:181]
	v_pk_mul_f32 v[110:111], v[110:111], v[182:183]
	v_pk_mul_f32 v[108:109], v[108:109], v[180:181]
	global_store_dwordx4 v[184:185], v[104:107], off offset:16
	v_pk_mul_f32 v[102:103], v[102:103], v[182:183]
	v_pk_mul_f32 v[100:101], v[100:101], v[180:181]
	v_lshl_add_u64 v[104:105], s[10:11], 0, v[226:227]
	v_pk_mul_f32 v[98:99], v[98:99], v[178:179]
	v_pk_mul_f32 v[96:97], v[96:97], v[176:177]
	v_pk_fma_f32 v[126:127], v[198:199], s[26:27], v[126:127] op_sel_hi:[1,0,1]
	v_pk_fma_f32 v[124:125], v[196:197], s[26:27], v[124:125] op_sel_hi:[1,0,1]
	v_pk_fma_f32 v[118:119], v[190:191], s[26:27], v[118:119] op_sel_hi:[1,0,1]
	v_pk_fma_f32 v[116:117], v[188:189], s[26:27], v[116:117] op_sel_hi:[1,0,1]
	v_pk_fma_f32 v[110:111], v[174:175], s[26:27], v[110:111] op_sel_hi:[1,0,1]
	v_pk_fma_f32 v[108:109], v[172:173], s[26:27], v[108:109] op_sel_hi:[1,0,1]
	v_lshl_add_u64 v[136:137], v[104:105], 0, v[216:217]
	v_pk_fma_f32 v[102:103], v[134:135], s[26:27], v[102:103] op_sel_hi:[1,0,1]
	v_pk_fma_f32 v[100:101], v[132:133], s[26:27], v[100:101] op_sel_hi:[1,0,1]
	v_pk_fma_f32 v[98:99], v[130:131], s[26:27], v[98:99] op_sel_hi:[1,0,1]
	v_pk_fma_f32 v[96:97], v[128:129], s[26:27], v[96:97] op_sel_hi:[1,0,1]
	global_store_dwordx4 v[214:215], v[124:127], off
	global_store_dwordx4 v[192:193], v[116:119], off
	global_store_dwordx4 v[184:185], v[108:111], off
	global_store_dwordx4 v[136:137], v[100:103], off
	global_store_dwordx4 v[136:137], v[96:99], off offset:16
	global_load_dwordx4 v[128:131], v[212:213], off
	global_load_dwordx4 v[132:135], v[212:213], off offset:16
	v_lshl_add_u64 v[138:139], s[10:11], 0, v[242:243]
	v_lshl_add_u64 v[138:139], v[138:139], 0, v[216:217]
	global_load_dwordx4 v[124:127], v[218:219], off offset:512
	global_load_dwordx4 v[120:123], v[218:219], off offset:528
	global_load_dwordx4 v[116:119], v[220:221], off offset:512
	global_load_dwordx4 v[112:115], v[220:221], off offset:528
	global_load_dwordx4 v[108:111], v[222:223], off offset:512
	global_load_dwordx4 v[104:107], v[222:223], off offset:528
	global_load_dwordx4 v[100:103], v[224:225], off offset:512
	global_load_dwordx4 v[96:99], v[224:225], off offset:528
	s_waitcnt vmcnt(8) lgkmcnt(0)
; #define EPIRES_LOAD(q_, buf_) do { const int bj_ = (q_) >> 1, ai_ = (q_) & 1; \
;             _Pragma("unroll") for (int m = 0; m < 4; ++m) { const float* xp = Xin + (size_t)(row0 + ai_ * HALF + m * 16) * D + col0 + bj_ * HALF; xa[buf_][m] = *(const f32x4*)xp; xb[buf_][m] = *(const f32x4*)(xp + 4); } } while (0)
;     __device__ __forceinline__ void operator()(const f32x4 (&acc)[2][2][4][2], const Unit& u, int wr, int wc, int fr, int fq) const {
;     ...
;         for (int q = 0; q < 4; ++q) { const int bj = q >> 1, ai = q & 1, co = col0 + bj * HALF, cb = q & 1;
;             if (q + 1 < 4) EPIRES_LOAD(q + 1, cb ^ 1);
;             const f32x4 g0 = *(const f32x4*)(gp + bj * HALF), g1 = *(const f32x4*)(gp + bj * HALF + 4);
;             f32x4 w0 = {1.f, 1.f, 1.f, 1.f}, w1 = w0, b0 = {0.f, 0.f, 0.f, 0.f}, b1 = b0;
;             if (stats) { w0 = *(const f32x4*)(lw + co); w1 = *(const f32x4*)(lw + co + 4); b0 = *(const f32x4*)(lb + co); b1 = *(const f32x4*)(lb + co + 4); }
; #pragma unroll
;             for (int m = 0; m < 4; ++m) { float* op = Xout + (size_t)(row0 + ai * HALF + m * 16) * D + co;
;                 f32x4 x0 = xa[cb][m], x1 = xb[cb][m];
;                 if (stats) { x0 = (x0 - st[ai][m].x) * st[ai][m].y * w0 + b0; x1 = (x1 - st[ai][m].x) * st[ai][m].y * w1 + b1; }
;                 *(f32x4*)op = x0 * ALPHA + g0 * acc[ai][bj][m][0]; *(f32x4*)(op + 4) = x1 * ALPHA + g1 * acc[ai][bj][m][1]; } }
	v_pk_mul_f32 v[94:95], v[94:95], v[130:131]
	v_pk_mul_f32 v[90:91], v[90:91], v[134:135]
	v_pk_mul_f32 v[88:89], v[88:89], v[132:133]
	v_pk_fma_f32 v[90:91], v[166:167], s[26:27], v[90:91] op_sel_hi:[1,0,1]
	v_pk_fma_f32 v[88:89], v[164:165], s[26:27], v[88:89] op_sel_hi:[1,0,1]
	global_store_dwordx4 v[138:139], v[88:91], off offset:16
	v_pk_mul_f32 v[82:83], v[82:83], v[134:135]
	v_pk_mul_f32 v[80:81], v[80:81], v[132:133]
	v_lshl_add_u64 v[88:89], s[10:11], 0, v[240:241]
	v_lshl_add_u64 v[164:165], v[88:89], 0, v[216:217]
	v_pk_fma_f32 v[82:83], v[158:159], s[26:27], v[82:83] op_sel_hi:[1,0,1]
	v_pk_fma_f32 v[80:81], v[156:157], s[26:27], v[80:81] op_sel_hi:[1,0,1]
	global_store_dwordx4 v[164:165], v[80:83], off offset:16
	v_pk_mul_f32 v[74:75], v[74:75], v[134:135]
	v_pk_mul_f32 v[72:73], v[72:73], v[132:133]
	v_lshl_add_u64 v[80:81], s[10:11], 0, v[238:239]
	v_lshl_add_u64 v[156:157], v[80:81], 0, v[216:217]
	v_pk_fma_f32 v[74:75], v[150:151], s[26:27], v[74:75] op_sel_hi:[1,0,1]
	v_pk_fma_f32 v[72:73], v[148:149], s[26:27], v[72:73] op_sel_hi:[1,0,1]
	v_pk_mul_f32 v[92:93], v[92:93], v[128:129]
	v_pk_mul_f32 v[86:87], v[86:87], v[130:131]
	v_pk_mul_f32 v[84:85], v[84:85], v[128:129]
	v_pk_mul_f32 v[78:79], v[78:79], v[130:131]
	v_pk_mul_f32 v[76:77], v[76:77], v[128:129]
	global_store_dwordx4 v[156:157], v[72:75], off offset:16
	v_pk_mul_f32 v[70:71], v[70:71], v[130:131]
	v_pk_mul_f32 v[68:69], v[68:69], v[128:129]
	v_lshl_add_u64 v[72:73], s[10:11], 0, v[236:237]
	v_pk_mul_f32 v[66:67], v[66:67], v[134:135]
	v_pk_mul_f32 v[64:65], v[64:65], v[132:133]
	v_pk_fma_f32 v[94:95], v[170:171], s[26:27], v[94:95] op_sel_hi:[1,0,1]
	v_pk_fma_f32 v[92:93], v[168:169], s[26:27], v[92:93] op_sel_hi:[1,0,1]
	v_pk_fma_f32 v[86:87], v[162:163], s[26:27], v[86:87] op_sel_hi:[1,0,1]
	v_pk_fma_f32 v[84:85], v[160:161], s[26:27], v[84:85] op_sel_hi:[1,0,1]
	v_pk_fma_f32 v[78:79], v[154:155], s[26:27], v[78:79] op_sel_hi:[1,0,1]
	v_pk_fma_f32 v[76:77], v[152:153], s[26:27], v[76:77] op_sel_hi:[1,0,1]
	v_lshl_add_u64 v[148:149], v[72:73], 0, v[216:217]
	v_pk_fma_f32 v[70:71], v[146:147], s[26:27], v[70:71] op_sel_hi:[1,0,1]
	v_pk_fma_f32 v[68:69], v[144:145], s[26:27], v[68:69] op_sel_hi:[1,0,1]
	v_pk_fma_f32 v[66:67], v[142:143], s[26:27], v[66:67] op_sel_hi:[1,0,1]
	v_pk_fma_f32 v[64:65], v[140:141], s[26:27], v[64:65] op_sel_hi:[1,0,1]
	global_store_dwordx4 v[138:139], v[92:95], off
	global_store_dwordx4 v[164:165], v[84:87], off
	global_store_dwordx4 v[156:157], v[76:79], off
	global_store_dwordx4 v[148:149], v[68:71], off
	global_store_dwordx4 v[148:149], v[64:67], off offset:16
	global_load_dwordx4 v[128:131], v[212:213], off offset:512
	global_load_dwordx4 v[132:135], v[212:213], off offset:528
	global_load_dwordx4 v[92:95], v[228:229], off offset:512
	global_load_dwordx4 v[88:91], v[228:229], off offset:528
	global_load_dwordx4 v[84:87], v[230:231], off offset:512
	global_load_dwordx4 v[80:83], v[230:231], off offset:528
	global_load_dwordx4 v[76:79], v[232:233], off offset:512
	global_load_dwordx4 v[72:75], v[232:233], off offset:528
	global_load_dwordx4 v[68:71], v[234:235], off offset:512
	global_load_dwordx4 v[64:67], v[234:235], off offset:528
	s_waitcnt vmcnt(8) lgkmcnt(0)
; #define EPIRES_LOAD(q_, buf_) do { const int bj_ = (q_) >> 1, ai_ = (q_) & 1; \
;             _Pragma("unroll") for (int m = 0; m < 4; ++m) { const float* xp = Xin + (size_t)(row0 + ai_ * HALF + m * 16) * D + col0 + bj_ * HALF; xa[buf_][m] = *(const f32x4*)xp; xb[buf_][m] = *(const f32x4*)(xp + 4); } } while (0)
; #define PG8_BAR __builtin_amdgcn_s_barrier()
;     __device__ __forceinline__ void operator()(const f32x4 (&acc)[2][2][4][2], const Unit& u, int wr, int wc, int fr, int fq) const {
;     ...
;         for (int q = 0; q < 4; ++q) { const int bj = q >> 1, ai = q & 1, co = col0 + bj * HALF, cb = q & 1;
;             if (q + 1 < 4) EPIRES_LOAD(q + 1, cb ^ 1);
;             const f32x4 g0 = *(const f32x4*)(gp + bj * HALF), g1 = *(const f32x4*)(gp + bj * HALF + 4);
;             f32x4 w0 = {1.f, 1.f, 1.f, 1.f}, w1 = w0, b0 = {0.f, 0.f, 0.f, 0.f}, b1 = b0;
;             if (stats) { w0 = *(const f32x4*)(lw + co); w1 = *(const f32x4*)(lw + co + 4); b0 = *(const f32x4*)(lb + co); b1 = *(const f32x4*)(lb + co + 4); }
; #pragma unroll
;             for (int m = 0; m < 4; ++m) { float* op = Xout + (size_t)(row0 + ai * HALF + m * 16) * D + co;
;                 f32x4 x0 = xa[cb][m], x1 = xb[cb][m];
;                 if (stats) { x0 = (x0 - st[ai][m].x) * st[ai][m].y * w0 + b0; x1 = (x1 - st[ai][m].x) * st[ai][m].y * w1 + b1; }
;                 *(f32x4*)op = x0 * ALPHA + g0 * acc[ai][bj][m][0]; *(f32x4*)(op + 4) = x1 * ALPHA + g1 * acc[ai][bj][m][1]; } }
; template <class Epi, bool ALIGN_EPI = true, bool SP2 = true>
; __device__ __forceinline__ void gemm_phase(LAS unsigned char* lds, const Gemm g, const StaticOrder& S, const Epi& E, const int wave_s) {
;     ...
;         if (!has_next) break;
; #pragma unroll
;         for (int a = 0; a < 2; ++a)
; #pragma unroll
;             for (int b = 0; b < 2; ++b)
; #pragma unroll
;                 for (int m = 0; m < 4; ++m)
; #pragma unroll
;                     for (int n = 0; n < 2; ++n) acc[a][b][m][n] = (f32x4){0.f, 0.f, 0.f, 0.f};
;         cur = nxt; cA = nA; cB = nB; ++ui;
;         if constexpr (ALIGN_EPI) { if (wr == 1) PG8_BAR; }
	v_pk_mul_f32 v[62:63], v[62:63], v[130:131]
	v_pk_mul_f32 v[60:61], v[60:61], v[128:129]
	v_pk_mul_f32 v[58:59], v[58:59], v[134:135]
	v_pk_mul_f32 v[56:57], v[56:57], v[132:133]
	v_pk_mul_f32 v[54:55], v[54:55], v[130:131]
	v_pk_mul_f32 v[52:53], v[52:53], v[128:129]
	v_pk_mul_f32 v[50:51], v[50:51], v[134:135]
	v_pk_mul_f32 v[48:49], v[48:49], v[132:133]
	v_pk_mul_f32 v[46:47], v[46:47], v[130:131]
	v_pk_mul_f32 v[44:45], v[44:45], v[128:129]
	v_pk_mul_f32 v[42:43], v[42:43], v[134:135]
	v_pk_mul_f32 v[40:41], v[40:41], v[132:133]
	v_pk_mul_f32 v[38:39], v[38:39], v[130:131]
	v_pk_mul_f32 v[36:37], v[36:37], v[128:129]
	v_pk_mul_f32 v[34:35], v[34:35], v[134:135]
	v_pk_mul_f32 v[32:33], v[32:33], v[132:133]
	v_pk_fma_f32 v[62:63], v[126:127], s[26:27], v[62:63] op_sel_hi:[1,0,1]
	v_pk_fma_f32 v[60:61], v[124:125], s[26:27], v[60:61] op_sel_hi:[1,0,1]
	v_pk_fma_f32 v[58:59], v[122:123], s[26:27], v[58:59] op_sel_hi:[1,0,1]
	v_pk_fma_f32 v[56:57], v[120:121], s[26:27], v[56:57] op_sel_hi:[1,0,1]
	v_pk_fma_f32 v[54:55], v[118:119], s[26:27], v[54:55] op_sel_hi:[1,0,1]
	v_pk_fma_f32 v[52:53], v[116:117], s[26:27], v[52:53] op_sel_hi:[1,0,1]
	v_pk_fma_f32 v[50:51], v[114:115], s[26:27], v[50:51] op_sel_hi:[1,0,1]
	v_pk_fma_f32 v[48:49], v[112:113], s[26:27], v[48:49] op_sel_hi:[1,0,1]
	v_pk_fma_f32 v[46:47], v[110:111], s[26:27], v[46:47] op_sel_hi:[1,0,1]
	v_pk_fma_f32 v[44:45], v[108:109], s[26:27], v[44:45] op_sel_hi:[1,0,1]
	v_pk_fma_f32 v[42:43], v[106:107], s[26:27], v[42:43] op_sel_hi:[1,0,1]
	v_pk_fma_f32 v[40:41], v[104:105], s[26:27], v[40:41] op_sel_hi:[1,0,1]
	v_pk_fma_f32 v[38:39], v[102:103], s[26:27], v[38:39] op_sel_hi:[1,0,1]
	v_pk_fma_f32 v[36:37], v[100:101], s[26:27], v[36:37] op_sel_hi:[1,0,1]
	v_pk_fma_f32 v[34:35], v[98:99], s[26:27], v[34:35] op_sel_hi:[1,0,1]
	v_pk_fma_f32 v[32:33], v[96:97], s[26:27], v[32:33] op_sel_hi:[1,0,1]
	global_store_dwordx4 v[214:215], v[60:63], off offset:512
	global_store_dwordx4 v[214:215], v[56:59], off offset:528
	global_store_dwordx4 v[192:193], v[52:55], off offset:512
	global_store_dwordx4 v[192:193], v[48:51], off offset:528
	global_store_dwordx4 v[184:185], v[44:47], off offset:512
	global_store_dwordx4 v[184:185], v[40:43], off offset:528
	global_store_dwordx4 v[136:137], v[36:39], off offset:512
	global_store_dwordx4 v[136:137], v[32:35], off offset:528
	global_load_dwordx4 v[32:35], v[212:213], off offset:512
	s_nop 0
	global_load_dwordx4 v[36:39], v[212:213], off offset:528
	s_waitcnt vmcnt(0) lgkmcnt(0)
	v_pk_mul_f32 v[30:31], v[30:31], v[34:35]
	v_pk_mul_f32 v[28:29], v[28:29], v[32:33]
	v_pk_mul_f32 v[26:27], v[26:27], v[38:39]
	v_pk_mul_f32 v[24:25], v[24:25], v[36:37]
	v_pk_mul_f32 v[22:23], v[22:23], v[34:35]
	v_pk_mul_f32 v[20:21], v[20:21], v[32:33]
	v_pk_mul_f32 v[18:19], v[18:19], v[38:39]
	v_pk_mul_f32 v[16:17], v[16:17], v[36:37]
	v_pk_mul_f32 v[14:15], v[14:15], v[34:35]
	v_pk_mul_f32 v[12:13], v[12:13], v[32:33]
	v_pk_mul_f32 v[6:7], v[6:7], v[34:35]
	v_pk_mul_f32 v[4:5], v[4:5], v[32:33]
	v_pk_mul_f32 v[2:3], v[2:3], v[38:39]
	v_pk_mul_f32 v[0:1], v[0:1], v[36:37]
	v_pk_fma_f32 v[30:31], v[94:95], s[26:27], v[30:31] op_sel_hi:[1,0,1]
	v_pk_fma_f32 v[28:29], v[92:93], s[26:27], v[28:29] op_sel_hi:[1,0,1]
	v_pk_fma_f32 v[26:27], v[90:91], s[26:27], v[26:27] op_sel_hi:[1,0,1]
	v_pk_fma_f32 v[24:25], v[88:89], s[26:27], v[24:25] op_sel_hi:[1,0,1]
	v_pk_fma_f32 v[22:23], v[86:87], s[26:27], v[22:23] op_sel_hi:[1,0,1]
	v_pk_fma_f32 v[20:21], v[84:85], s[26:27], v[20:21] op_sel_hi:[1,0,1]
	v_pk_fma_f32 v[18:19], v[82:83], s[26:27], v[18:19] op_sel_hi:[1,0,1]
	v_pk_fma_f32 v[16:17], v[80:81], s[26:27], v[16:17] op_sel_hi:[1,0,1]
	v_pk_fma_f32 v[14:15], v[78:79], s[26:27], v[14:15] op_sel_hi:[1,0,1]
	v_pk_fma_f32 v[12:13], v[76:77], s[26:27], v[12:13] op_sel_hi:[1,0,1]
	v_pk_mul_f32 v[10:11], v[10:11], v[38:39]
	v_pk_mul_f32 v[8:9], v[8:9], v[36:37]
	v_pk_fma_f32 v[6:7], v[70:71], s[26:27], v[6:7] op_sel_hi:[1,0,1]
	v_pk_fma_f32 v[4:5], v[68:69], s[26:27], v[4:5] op_sel_hi:[1,0,1]
	v_pk_fma_f32 v[2:3], v[66:67], s[26:27], v[2:3] op_sel_hi:[1,0,1]
	v_pk_fma_f32 v[0:1], v[64:65], s[26:27], v[0:1] op_sel_hi:[1,0,1]
	global_store_dwordx4 v[138:139], v[28:31], off offset:512
	global_store_dwordx4 v[138:139], v[24:27], off offset:528
	global_store_dwordx4 v[164:165], v[20:23], off offset:512
	global_store_dwordx4 v[164:165], v[16:19], off offset:528
	v_pk_fma_f32 v[10:11], v[74:75], s[26:27], v[10:11] op_sel_hi:[1,0,1]
	v_pk_fma_f32 v[8:9], v[72:73], s[26:27], v[8:9] op_sel_hi:[1,0,1]
	global_store_dwordx4 v[156:157], v[12:15], off offset:512
	global_store_dwordx4 v[156:157], v[8:11], off offset:528
	global_store_dwordx4 v[148:149], v[4:7], off offset:512
	global_store_dwordx4 v[148:149], v[0:3], off offset:528
	s_cbranch_vccnz .LBB0_469
	s_andn2_b64 vcc, exec, s[8:9]
	s_cbranch_vccnz .LBB0_468
	s_barrier
	s_branch .LBB0_468
